# final RMSNorm loop and P0 x->bf16 loop: loads batched per row with counted vmcnt, next row prefetched in the norm loop
# baseline (speedup 1.0000x reference)
; DEV void st4(bf16_t* p, f32x4 v) { u32x2 w; w.x = pk2(v[0], v[1]); w.y = pk2(v[2], v[3]); *(u32x2*)p = w; }
; DEV u64_t ss_fix(float v) { return (u64_t)(v * 16777216.f + 0.5f); }
; __global__ void __launch_bounds__(512, 2) mega(Params p_unused) {
;     ...
;         for (int row = gw; row < T; row += NGW) {
;             const f32x4* xr = (const f32x4*)(x + (size_t)row * D) + lane; float ss = 0.f;
; #pragma unroll
;             for (int j = 0; j < 4; ++j) { const f32x4 v = xr[64 * j]; ss += (v[0] * v[0] + v[1] * v[1]) + (v[2] * v[2] + v[3] * v[3]);
;                 st4(XB + (size_t)row * D + (lane + 64 * j) * 4, v); }
;             ss = wave_sum(ss); if (lane == 0) SS[row] = ss_fix(ss);
;         }
.LBB0_7:
	s_waitcnt lgkmcnt(0)
	global_load_dwordx4 v[18:21], v[10:11], off
	global_load_dwordx4 v[22:25], v[10:11], off offset:1024
	global_load_dwordx4 v[26:29], v[10:11], off offset:2048
	global_load_dwordx4 v[30:33], v[10:11], off offset:3072
	s_waitcnt vmcnt(3)
	v_cvt_pk_bf16_f32 v34, v18, v19
	v_cvt_pk_bf16_f32 v35, v20, v21
	global_store_dwordx2 v[6:7], v[34:35], off
	s_waitcnt vmcnt(3)
	v_cvt_pk_bf16_f32 v36, v22, v23
	v_cvt_pk_bf16_f32 v37, v24, v25
	global_store_dwordx2 v[6:7], v[36:37], off offset:512
	s_waitcnt vmcnt(3)
	v_cvt_pk_bf16_f32 v38, v26, v27
	v_cvt_pk_bf16_f32 v39, v28, v29
	global_store_dwordx2 v[6:7], v[38:39], off offset:1024
	v_cmp_lt_i32_e64 s[6:7], v5, v17
	v_mul_f32_e32 v19, v19, v19
	v_mul_f32_e32 v21, v21, v21
	v_fmac_f32_e32 v19, v18, v18
	v_fmac_f32_e32 v21, v20, v20
	v_add_f32_e32 v18, v19, v21
	v_mul_f32_e32 v19, v23, v23
	v_mul_f32_e32 v20, v25, v25
	v_fmac_f32_e32 v19, v22, v22
	v_fmac_f32_e32 v20, v24, v24
	v_add_f32_e32 v19, v19, v20
	v_add_f32_e32 v18, v18, v19
	v_mul_f32_e32 v19, v27, v27
	v_mul_f32_e32 v20, v29, v29
	v_fmac_f32_e32 v19, v26, v26
	v_fmac_f32_e32 v20, v28, v28
	v_add_f32_e32 v19, v19, v20
	v_add_f32_e32 v18, v18, v19
	s_waitcnt vmcnt(3)
	v_mul_f32_e32 v19, v31, v31
	v_mul_f32_e32 v20, v33, v33
	v_fmac_f32_e32 v19, v30, v30
	v_fmac_f32_e32 v20, v32, v32
	v_cndmask_b32_e64 v9, v3, v5, s[6:7]
	v_add_f32_e32 v19, v19, v20
	v_lshlrev_b32_e32 v9, 2, v9
	v_add_f32_e32 v18, v18, v19
	ds_bpermute_b32 v9, v9, v18
	v_cmp_lt_i32_e64 s[6:7], v12, v17
	v_cvt_pk_bf16_f32 v20, v30, v31
	v_cvt_pk_bf16_f32 v21, v32, v33
	global_store_dwordx2 v[6:7], v[20:21], off offset:1536
	s_waitcnt lgkmcnt(0)
	v_add_f32_e32 v9, v18, v9
	v_cndmask_b32_e64 v19, v3, v12, s[6:7]
	v_lshlrev_b32_e32 v19, 2, v19
	ds_bpermute_b32 v18, v19, v9
	v_cmp_lt_i32_e64 s[6:7], v13, v17
	s_waitcnt lgkmcnt(0)
	v_add_f32_e32 v9, v9, v18
	v_cndmask_b32_e64 v19, v3, v13, s[6:7]
	v_lshlrev_b32_e32 v19, 2, v19
	ds_bpermute_b32 v18, v19, v9
	v_cmp_lt_i32_e64 s[6:7], v14, v17
	s_waitcnt lgkmcnt(0)
	v_add_f32_e32 v9, v9, v18
	v_cndmask_b32_e64 v19, v3, v14, s[6:7]
	v_lshlrev_b32_e32 v19, 2, v19
	ds_bpermute_b32 v18, v19, v9
	v_cmp_lt_i32_e64 s[6:7], v15, v17
	s_waitcnt lgkmcnt(0)
	v_add_f32_e32 v9, v9, v18
	v_cndmask_b32_e64 v19, v3, v15, s[6:7]
	v_lshlrev_b32_e32 v19, 2, v19
	ds_bpermute_b32 v18, v19, v9
	v_cmp_lt_i32_e64 s[6:7], v16, v17
	s_waitcnt lgkmcnt(0)
	v_add_f32_e32 v9, v9, v18
	v_cndmask_b32_e64 v19, v3, v16, s[6:7]
	v_lshlrev_b32_e32 v18, 2, v19
	ds_bpermute_b32 v18, v18, v9
	s_and_saveexec_b64 s[4:5], vcc
	s_cbranch_execz .LBB0_6
	s_waitcnt lgkmcnt(0)
	v_add_f32_e32 v9, v9, v18
	v_fma_f32 v9, v9, s1, 0.5
	v_trunc_f32_e32 v9, v9
	v_mul_f32_e32 v18, 0x2f800000, v9
	v_floor_f32_e32 v19, v18
	v_fmac_f32_e32 v9, 0xcf800000, v19
	v_cvt_u32_f32_e32 v18, v9
	v_cvt_u32_f32_e32 v19, v19
	v_mov_b64_e32 v[20:21], s[10:11]
	global_store_dwordx2 v[20:21], v[18:19], off
	s_branch .LBB0_6

; DEV float rstd_of(const unsigned long long* ss, int row, float invn) { return rsqrtf((float)ss[row] * (1.f / 16777216.f) * invn + EPS); }
; DEV unsigned char* launder(unsigned char* p) { unsigned lo = __builtin_amdgcn_readfirstlane((unsigned)(uintptr_t)p), hi = __builtin_amdgcn_readfirstlane((unsigned)((uintptr_t)p >> 32)); asm volatile("" : "+s"(lo), "+s"(hi)); return (unsigned char*)(((uintptr_t)hi << 32) | (uintptr_t)lo); }
; DEV const Params* kparams() { const Params* q = (const Params*)__builtin_amdgcn_kernarg_segment_ptr(); asm volatile("" : "+s"(q)); return q; }
; __global__ void __launch_bounds__(512, 2) mega(Params p_unused) {
;     ...
;         TIDS const Params& p = *kparams(); unsigned char* w = launder(p.ws); float* X = p.out; const u64_t* ssf = SSP(w, 10);
;         for (int row = blockIdx.x * 8 + wid; row < T; row += gridDim.x * 8) {
;             const float rs = rstd_of(ssf, row, 1.f / 1024.f); f32x4* xr = (f32x4*)(X + (size_t)row * D) + lane;
; #pragma unroll
;             for (int j = 0; j < 4; ++j) { const f32x4 g = *((const f32x4*)p.in[25] + lane + 64 * j); xr[64 * j] = xr[64 * j] * rs * g; }
;         }
.LBB0_2044:
	v_readlane_b32 s1, v254, 4
	v_mov_b64_e32 v[0:1], s[86:87]
	flat_load_dwordx2 v[0:1], v[0:1] offset:216
	v_readfirstlane_b32 s0, v224
	s_ashr_i32 s0, s0, 6
	s_add_i32 s2, s0, s1
	s_cmpk_gt_i32 s2, 0x7fff
	s_waitcnt vmcnt(0) lgkmcnt(0)
	v_readfirstlane_b32 s0, v0
	v_readfirstlane_b32 s3, v1
	s_cbranch_scc1 .LBB0_2047
	v_mov_b64_e32 v[0:1], s[86:87]
	flat_load_dwordx2 v[4:5], v[0:1] offset:208
	v_and_b32_e32 v8, 63, v224
	s_add_u32 s0, s0, 0x1f880000
	v_mov_b32_e32 v3, 0
	v_lshlrev_b32_e32 v2, 4, v8
	v_mov_b32_e32 v6, 0x358637bd
	s_mov_b32 s1, 0x800000
	s_addc_u32 s4, s3, 0
	s_waitcnt vmcnt(0) lgkmcnt(0)
	v_lshl_add_u64 v[4:5], v[4:5], 0, v[2:3]
	v_lshlrev_b32_e32 v2, 4, v8
	flat_load_dwordx2 v[12:13], v[0:1] offset:200
	s_waitcnt vmcnt(0) lgkmcnt(0)
	v_lshl_add_u64 v[12:13], v[12:13], 0, v[2:3]
	global_load_dwordx4 v[32:35], v[12:13], off
	global_load_dwordx4 v[36:39], v[12:13], off offset:1024
	global_load_dwordx4 v[40:43], v[12:13], off offset:2048
	global_load_dwordx4 v[44:47], v[12:13], off offset:3072
	s_ashr_i32 s3, s2, 31
	s_mov_b32 s10, s2
	s_mov_b32 s11, s3
	s_lshl_b64 s[6:7], s[10:11], 3
	s_add_u32 s6, s0, s6
	s_addc_u32 s7, s4, s7
	v_mov_b64_e32 v[16:17], s[6:7]
	global_load_dwordx2 v[16:17], v[16:17], off
	s_lshl_b64 s[6:7], s[10:11], 12
	v_lshl_add_u64 v[20:21], v[4:5], 0, s[6:7]
	global_load_dwordx4 v[48:51], v[20:21], off
	global_load_dwordx4 v[52:55], v[20:21], off offset:1024
	global_load_dwordx4 v[56:59], v[20:21], off offset:2048
	global_load_dwordx4 v[60:63], v[20:21], off offset:3072
	s_add_i32 s8, s2, s40
	s_cmpk_gt_i32 s8, 0x7fff
	s_cbranch_scc1 .Lfn_lastA
	s_ashr_i32 s3, s8, 31
	s_mov_b32 s10, s8
	s_mov_b32 s11, s3
	s_lshl_b64 s[6:7], s[10:11], 3
	s_add_u32 s6, s0, s6
	s_addc_u32 s7, s4, s7
	v_mov_b64_e32 v[18:19], s[6:7]
	global_load_dwordx2 v[18:19], v[18:19], off
	s_lshl_b64 s[6:7], s[10:11], 12
	v_lshl_add_u64 v[24:25], v[4:5], 0, s[6:7]
	global_load_dwordx4 v[64:67], v[24:25], off
	global_load_dwordx4 v[68:71], v[24:25], off offset:1024
	global_load_dwordx4 v[72:75], v[24:25], off offset:2048
	global_load_dwordx4 v[76:79], v[24:25], off offset:3072
	s_waitcnt vmcnt(9)
	v_ffbh_u32_e32 v7, v17
	v_min_u32_e32 v7, 32, v7
	v_lshlrev_b64 v[16:17], v7, v[16:17]
	v_min_u32_e32 v16, 1, v16
	v_or_b32_e32 v16, v17, v16
	v_cvt_f32_u32_e32 v16, v16
	v_sub_u32_e32 v7, 32, v7
	v_ldexp_f32 v7, v16, v7
	v_mul_f32_e32 v7, 0x33800000, v7
	v_fmamk_f32 v7, v7, 0x3a800000, v6
	v_mul_f32_e32 v16, 0x4b800000, v7
	v_cmp_gt_f32_e32 vcc, s1, v7
	s_nop 1
	v_cndmask_b32_e32 v7, v7, v16, vcc
	v_rsq_f32_e32 v7, v7
	s_nop 0
	v_mul_f32_e32 v22, 0x45800000, v7
	v_cndmask_b32_e32 v22, v7, v22, vcc
	s_waitcnt vmcnt(5)
	v_pk_mul_f32 v[48:49], v[22:23], v[48:49] op_sel_hi:[0,1]
	v_pk_mul_f32 v[50:51], v[22:23], v[50:51] op_sel_hi:[0,1]
	v_pk_mul_f32 v[48:49], v[32:33], v[48:49]
	v_pk_mul_f32 v[50:51], v[34:35], v[50:51]
	global_store_dwordx4 v[20:21], v[48:51], off
	v_pk_mul_f32 v[52:53], v[22:23], v[52:53] op_sel_hi:[0,1]
	v_pk_mul_f32 v[54:55], v[22:23], v[54:55] op_sel_hi:[0,1]
	v_pk_mul_f32 v[52:53], v[36:37], v[52:53]
	v_pk_mul_f32 v[54:55], v[38:39], v[54:55]
	global_store_dwordx4 v[20:21], v[52:55], off offset:1024
	v_pk_mul_f32 v[56:57], v[22:23], v[56:57] op_sel_hi:[0,1]
	v_pk_mul_f32 v[58:59], v[22:23], v[58:59] op_sel_hi:[0,1]
	v_pk_mul_f32 v[56:57], v[40:41], v[56:57]
	v_pk_mul_f32 v[58:59], v[42:43], v[58:59]
	global_store_dwordx4 v[20:21], v[56:59], off offset:2048
	v_pk_mul_f32 v[60:61], v[22:23], v[60:61] op_sel_hi:[0,1]
	v_pk_mul_f32 v[62:63], v[22:23], v[62:63] op_sel_hi:[0,1]
	v_pk_mul_f32 v[60:61], v[44:45], v[60:61]
	v_pk_mul_f32 v[62:63], v[46:47], v[62:63]
	global_store_dwordx4 v[20:21], v[60:63], off offset:3072
.Lfn_loop:
	s_add_i32 s2, s8, s40
	s_cmpk_gt_i32 s2, 0x7fff
	s_cbranch_scc1 .Lfn_lastB
	s_ashr_i32 s3, s2, 31
	s_mov_b32 s10, s2
	s_mov_b32 s11, s3
	s_lshl_b64 s[6:7], s[10:11], 3
	s_add_u32 s6, s0, s6
	s_addc_u32 s7, s4, s7
	v_mov_b64_e32 v[16:17], s[6:7]
	global_load_dwordx2 v[16:17], v[16:17], off
	s_lshl_b64 s[6:7], s[10:11], 12
	v_lshl_add_u64 v[20:21], v[4:5], 0, s[6:7]
	global_load_dwordx4 v[48:51], v[20:21], off
	global_load_dwordx4 v[52:55], v[20:21], off offset:1024
	global_load_dwordx4 v[56:59], v[20:21], off offset:2048
	global_load_dwordx4 v[60:63], v[20:21], off offset:3072
	s_waitcnt vmcnt(13)
	v_ffbh_u32_e32 v7, v19
	v_min_u32_e32 v7, 32, v7
	v_lshlrev_b64 v[18:19], v7, v[18:19]
	v_min_u32_e32 v18, 1, v18
	v_or_b32_e32 v18, v19, v18
	v_cvt_f32_u32_e32 v18, v18
	v_sub_u32_e32 v7, 32, v7
	v_ldexp_f32 v7, v18, v7
	v_mul_f32_e32 v7, 0x33800000, v7
	v_fmamk_f32 v7, v7, 0x3a800000, v6
	v_mul_f32_e32 v18, 0x4b800000, v7
	v_cmp_gt_f32_e32 vcc, s1, v7
	s_nop 1
	v_cndmask_b32_e32 v7, v7, v18, vcc
	v_rsq_f32_e32 v7, v7
	s_nop 0
	v_mul_f32_e32 v22, 0x45800000, v7
	v_cndmask_b32_e32 v22, v7, v22, vcc
	s_waitcnt vmcnt(9)
	v_pk_mul_f32 v[64:65], v[22:23], v[64:65] op_sel_hi:[0,1]
	v_pk_mul_f32 v[66:67], v[22:23], v[66:67] op_sel_hi:[0,1]
	v_pk_mul_f32 v[64:65], v[32:33], v[64:65]
	v_pk_mul_f32 v[66:67], v[34:35], v[66:67]
	global_store_dwordx4 v[24:25], v[64:67], off
	v_pk_mul_f32 v[68:69], v[22:23], v[68:69] op_sel_hi:[0,1]
	v_pk_mul_f32 v[70:71], v[22:23], v[70:71] op_sel_hi:[0,1]
	v_pk_mul_f32 v[68:69], v[36:37], v[68:69]
	v_pk_mul_f32 v[70:71], v[38:39], v[70:71]
	global_store_dwordx4 v[24:25], v[68:71], off offset:1024
	v_pk_mul_f32 v[72:73], v[22:23], v[72:73] op_sel_hi:[0,1]
	v_pk_mul_f32 v[74:75], v[22:23], v[74:75] op_sel_hi:[0,1]
	v_pk_mul_f32 v[72:73], v[40:41], v[72:73]
	v_pk_mul_f32 v[74:75], v[42:43], v[74:75]
	global_store_dwordx4 v[24:25], v[72:75], off offset:2048
	v_pk_mul_f32 v[76:77], v[22:23], v[76:77] op_sel_hi:[0,1]
	v_pk_mul_f32 v[78:79], v[22:23], v[78:79] op_sel_hi:[0,1]
	v_pk_mul_f32 v[76:77], v[44:45], v[76:77]
	v_pk_mul_f32 v[78:79], v[46:47], v[78:79]
	global_store_dwordx4 v[24:25], v[76:79], off offset:3072
	s_add_i32 s8, s2, s40
	s_cmpk_gt_i32 s8, 0x7fff
	s_cbranch_scc1 .Lfn_lastA
; DEV float rstd_of(const unsigned long long* ss, int row, float invn) { return rsqrtf((float)ss[row] * (1.f / 16777216.f) * invn + EPS); }
; DEV unsigned char* launder(unsigned char* p) { unsigned lo = __builtin_amdgcn_readfirstlane((unsigned)(uintptr_t)p), hi = __builtin_amdgcn_readfirstlane((unsigned)((uintptr_t)p >> 32)); asm volatile("" : "+s"(lo), "+s"(hi)); return (unsigned char*)(((uintptr_t)hi << 32) | (uintptr_t)lo); }
; DEV const Params* kparams() { const Params* q = (const Params*)__builtin_amdgcn_kernarg_segment_ptr(); asm volatile("" : "+s"(q)); return q; }
; __global__ void __launch_bounds__(512, 2) mega(Params p_unused) {
;     ...
;         TIDS const Params& p = *kparams(); unsigned char* w = launder(p.ws); float* X = p.out; const u64_t* ssf = SSP(w, 10);
;         for (int row = blockIdx.x * 8 + wid; row < T; row += gridDim.x * 8) {
;             const float rs = rstd_of(ssf, row, 1.f / 1024.f); f32x4* xr = (f32x4*)(X + (size_t)row * D) + lane;
; #pragma unroll
;             for (int j = 0; j < 4; ++j) { const f32x4 g = *((const f32x4*)p.in[25] + lane + 64 * j); xr[64 * j] = xr[64 * j] * rs * g; }
;         }
	s_ashr_i32 s3, s8, 31
	s_mov_b32 s10, s8
	s_mov_b32 s11, s3
	s_lshl_b64 s[6:7], s[10:11], 3
	s_add_u32 s6, s0, s6
	s_addc_u32 s7, s4, s7
	v_mov_b64_e32 v[18:19], s[6:7]
	global_load_dwordx2 v[18:19], v[18:19], off
	s_lshl_b64 s[6:7], s[10:11], 12
	v_lshl_add_u64 v[24:25], v[4:5], 0, s[6:7]
	global_load_dwordx4 v[64:67], v[24:25], off
	global_load_dwordx4 v[68:71], v[24:25], off offset:1024
	global_load_dwordx4 v[72:75], v[24:25], off offset:2048
	global_load_dwordx4 v[76:79], v[24:25], off offset:3072
	s_waitcnt vmcnt(13)
	v_ffbh_u32_e32 v7, v17
	v_min_u32_e32 v7, 32, v7
	v_lshlrev_b64 v[16:17], v7, v[16:17]
	v_min_u32_e32 v16, 1, v16
	v_or_b32_e32 v16, v17, v16
	v_cvt_f32_u32_e32 v16, v16
	v_sub_u32_e32 v7, 32, v7
	v_ldexp_f32 v7, v16, v7
	v_mul_f32_e32 v7, 0x33800000, v7
	v_fmamk_f32 v7, v7, 0x3a800000, v6
	v_mul_f32_e32 v16, 0x4b800000, v7
	v_cmp_gt_f32_e32 vcc, s1, v7
	s_nop 1
	v_cndmask_b32_e32 v7, v7, v16, vcc
	v_rsq_f32_e32 v7, v7
	s_nop 0
	v_mul_f32_e32 v22, 0x45800000, v7
	v_cndmask_b32_e32 v22, v7, v22, vcc
	s_waitcnt vmcnt(9)
	v_pk_mul_f32 v[48:49], v[22:23], v[48:49] op_sel_hi:[0,1]
	v_pk_mul_f32 v[50:51], v[22:23], v[50:51] op_sel_hi:[0,1]
	v_pk_mul_f32 v[48:49], v[32:33], v[48:49]
	v_pk_mul_f32 v[50:51], v[34:35], v[50:51]
	global_store_dwordx4 v[20:21], v[48:51], off
	v_pk_mul_f32 v[52:53], v[22:23], v[52:53] op_sel_hi:[0,1]
	v_pk_mul_f32 v[54:55], v[22:23], v[54:55] op_sel_hi:[0,1]
	v_pk_mul_f32 v[52:53], v[36:37], v[52:53]
	v_pk_mul_f32 v[54:55], v[38:39], v[54:55]
	global_store_dwordx4 v[20:21], v[52:55], off offset:1024
	v_pk_mul_f32 v[56:57], v[22:23], v[56:57] op_sel_hi:[0,1]
	v_pk_mul_f32 v[58:59], v[22:23], v[58:59] op_sel_hi:[0,1]
	v_pk_mul_f32 v[56:57], v[40:41], v[56:57]
	v_pk_mul_f32 v[58:59], v[42:43], v[58:59]
	global_store_dwordx4 v[20:21], v[56:59], off offset:2048
	v_pk_mul_f32 v[60:61], v[22:23], v[60:61] op_sel_hi:[0,1]
	v_pk_mul_f32 v[62:63], v[22:23], v[62:63] op_sel_hi:[0,1]
	v_pk_mul_f32 v[60:61], v[44:45], v[60:61]
	v_pk_mul_f32 v[62:63], v[46:47], v[62:63]
	global_store_dwordx4 v[20:21], v[60:63], off offset:3072
	s_branch .Lfn_loop
.Lfn_lastA:
	s_waitcnt vmcnt(0)
	v_ffbh_u32_e32 v7, v17
	v_min_u32_e32 v7, 32, v7
	v_lshlrev_b64 v[16:17], v7, v[16:17]
	v_min_u32_e32 v16, 1, v16
	v_or_b32_e32 v16, v17, v16
	v_cvt_f32_u32_e32 v16, v16
	v_sub_u32_e32 v7, 32, v7
	v_ldexp_f32 v7, v16, v7
	v_mul_f32_e32 v7, 0x33800000, v7
	v_fmamk_f32 v7, v7, 0x3a800000, v6
	v_mul_f32_e32 v16, 0x4b800000, v7
	v_cmp_gt_f32_e32 vcc, s1, v7
	s_nop 1
	v_cndmask_b32_e32 v7, v7, v16, vcc
	v_rsq_f32_e32 v7, v7
	s_nop 0
	v_mul_f32_e32 v22, 0x45800000, v7
	v_cndmask_b32_e32 v22, v7, v22, vcc
	s_nop 0
	v_pk_mul_f32 v[48:49], v[22:23], v[48:49] op_sel_hi:[0,1]
	v_pk_mul_f32 v[50:51], v[22:23], v[50:51] op_sel_hi:[0,1]
	v_pk_mul_f32 v[48:49], v[32:33], v[48:49]
	v_pk_mul_f32 v[50:51], v[34:35], v[50:51]
	global_store_dwordx4 v[20:21], v[48:51], off
	v_pk_mul_f32 v[52:53], v[22:23], v[52:53] op_sel_hi:[0,1]
	v_pk_mul_f32 v[54:55], v[22:23], v[54:55] op_sel_hi:[0,1]
	v_pk_mul_f32 v[52:53], v[36:37], v[52:53]
	v_pk_mul_f32 v[54:55], v[38:39], v[54:55]
	global_store_dwordx4 v[20:21], v[52:55], off offset:1024
	v_pk_mul_f32 v[56:57], v[22:23], v[56:57] op_sel_hi:[0,1]
	v_pk_mul_f32 v[58:59], v[22:23], v[58:59] op_sel_hi:[0,1]
	v_pk_mul_f32 v[56:57], v[40:41], v[56:57]
	v_pk_mul_f32 v[58:59], v[42:43], v[58:59]
	global_store_dwordx4 v[20:21], v[56:59], off offset:2048
	v_pk_mul_f32 v[60:61], v[22:23], v[60:61] op_sel_hi:[0,1]
	v_pk_mul_f32 v[62:63], v[22:23], v[62:63] op_sel_hi:[0,1]
	v_pk_mul_f32 v[60:61], v[44:45], v[60:61]
	v_pk_mul_f32 v[62:63], v[46:47], v[62:63]
	global_store_dwordx4 v[20:21], v[60:63], off offset:3072
	s_branch .LBB0_2047
.Lfn_lastB:
	s_waitcnt vmcnt(0)
	v_ffbh_u32_e32 v7, v19
	v_min_u32_e32 v7, 32, v7
	v_lshlrev_b64 v[18:19], v7, v[18:19]
	v_min_u32_e32 v18, 1, v18
	v_or_b32_e32 v18, v19, v18
	v_cvt_f32_u32_e32 v18, v18
	v_sub_u32_e32 v7, 32, v7
	v_ldexp_f32 v7, v18, v7
	v_mul_f32_e32 v7, 0x33800000, v7
	v_fmamk_f32 v7, v7, 0x3a800000, v6
	v_mul_f32_e32 v18, 0x4b800000, v7
	v_cmp_gt_f32_e32 vcc, s1, v7
	s_nop 1
	v_cndmask_b32_e32 v7, v7, v18, vcc
	v_rsq_f32_e32 v7, v7
	s_nop 0
	v_mul_f32_e32 v22, 0x45800000, v7
	v_cndmask_b32_e32 v22, v7, v22, vcc
	s_nop 0
	v_pk_mul_f32 v[64:65], v[22:23], v[64:65] op_sel_hi:[0,1]
	v_pk_mul_f32 v[66:67], v[22:23], v[66:67] op_sel_hi:[0,1]
	v_pk_mul_f32 v[64:65], v[32:33], v[64:65]
	v_pk_mul_f32 v[66:67], v[34:35], v[66:67]
	global_store_dwordx4 v[24:25], v[64:67], off
	v_pk_mul_f32 v[68:69], v[22:23], v[68:69] op_sel_hi:[0,1]
	v_pk_mul_f32 v[70:71], v[22:23], v[70:71] op_sel_hi:[0,1]
	v_pk_mul_f32 v[68:69], v[36:37], v[68:69]
	v_pk_mul_f32 v[70:71], v[38:39], v[70:71]
	global_store_dwordx4 v[24:25], v[68:71], off offset:1024
	v_pk_mul_f32 v[72:73], v[22:23], v[72:73] op_sel_hi:[0,1]
	v_pk_mul_f32 v[74:75], v[22:23], v[74:75] op_sel_hi:[0,1]
	v_pk_mul_f32 v[72:73], v[40:41], v[72:73]
	v_pk_mul_f32 v[74:75], v[42:43], v[74:75]
	global_store_dwordx4 v[24:25], v[72:75], off offset:2048
	v_pk_mul_f32 v[76:77], v[22:23], v[76:77] op_sel_hi:[0,1]
	v_pk_mul_f32 v[78:79], v[22:23], v[78:79] op_sel_hi:[0,1]
	v_pk_mul_f32 v[76:77], v[44:45], v[76:77]
	v_pk_mul_f32 v[78:79], v[46:47], v[78:79]
	global_store_dwordx4 v[24:25], v[76:79], off offset:3072
